# neighbourhood attention: softmax row sums via two-pass 4x4x4 bf16 MFMAs into four lane-local accumulators (rescaled with the l registers), folded with a permlane at unit end; on top of the diff-loop 4
# speedup vs baseline: 1.0109x; 1.0036x over previous
.Lna_547:
	v_exp_f32_e32 v15, v144
	v_exp_f32_e32 v144, v128
	v_exp_f32_e32 v128, v145
	v_exp_f32_e32 v129, v129
	v_exp_f32_e32 v145, v146
	v_exp_f32_e32 v130, v130
	v_exp_f32_e32 v146, v147
	v_exp_f32_e32 v131, v131
	v_exp_f32_e32 v147, v148
	v_exp_f32_e32 v148, v132
	v_exp_f32_e32 v149, v149
	v_exp_f32_e32 v218, v133
	v_exp_f32_e32 v150, v150
	v_exp_f32_e32 v219, v134
	v_exp_f32_e32 v151, v151
	v_exp_f32_e32 v220, v135
	v_exp_f32_e32 v132, v152
	v_exp_f32_e32 v133, v136
	v_exp_f32_e32 v134, v153
	v_exp_f32_e32 v135, v137
	v_exp_f32_e32 v137, v154
	v_exp_f32_e32 v138, v138
	v_exp_f32_e32 v152, v155
	v_exp_f32_e32 v139, v139
	v_exp_f32_e32 v153, v156
	v_exp_f32_e32 v154, v140
	v_exp_f32_e32 v155, v157
	v_exp_f32_e32 v156, v141
	v_exp_f32_e32 v157, v158
	v_exp_f32_e32 v158, v142
	v_exp_f32_e32 v159, v159
	v_exp_f32_e32 v143, v143
	v_cvt_pk_bf16_f32 v128, v15, v128
	v_cvt_pk_bf16_f32 v132, v132, v134
	v_cvt_pk_bf16_f32 v136, v144, v129
	v_cvt_pk_bf16_f32 v140, v133, v135
	v_cvt_pk_bf16_f32 v129, v145, v146
	v_cvt_pk_bf16_f32 v133, v137, v152
	v_cvt_pk_bf16_f32 v137, v130, v131
	v_cvt_pk_bf16_f32 v141, v138, v139
	v_cvt_pk_bf16_f32 v130, v147, v149
	v_cvt_pk_bf16_f32 v134, v153, v155
	v_cvt_pk_bf16_f32 v138, v148, v218
	v_cvt_pk_bf16_f32 v142, v154, v156
	v_cvt_pk_bf16_f32 v131, v150, v151
	v_cvt_pk_bf16_f32 v135, v157, v159
	v_cvt_pk_bf16_f32 v139, v219, v220
	v_cvt_pk_bf16_f32 v143, v158, v143
	ds_read_b64_tr_b16 v[144:145], v0 offset:12288
	ds_read_b64_tr_b16 v[146:147], v0 offset:12800
	ds_read_b64_tr_b16 v[148:149], v0 offset:13312
	ds_read_b64_tr_b16 v[150:151], v0 offset:13824
	ds_read_b64_tr_b16 v[152:153], v0 offset:14336
	ds_read_b64_tr_b16 v[154:155], v0 offset:14848
	ds_read_b64_tr_b16 v[156:157], v0 offset:15360
	ds_read_b64_tr_b16 v[158:159], v0 offset:15872
	s_setprio 1
	s_waitcnt lgkmcnt(8)
	v_mfma_f32_32x32x16_bf16 v[16:31], v[192:195], v[128:131], v[16:31]
	v_mfma_f32_32x32x16_bf16 v[16:31], v[10:13], v[132:135], v[16:31]
	v_mfma_f32_32x32x16_bf16 v[16:31], v[6:9], v[136:139], v[16:31]
	v_mfma_f32_32x32x16_bf16 v[16:31], v[2:5], v[140:143], v[16:31]
	v_mfma_f32_4x4x4_16b_bf16 v[48:51], v[116:117], v[128:129], v[48:51]
	v_mfma_f32_4x4x4_16b_bf16 v[52:55], v[116:117], v[130:131], v[52:55]
	s_waitcnt lgkmcnt(6)
	v_mfma_f32_32x32x16_bf16 v[32:47], v[144:147], v[128:131], v[32:47]
	v_mfma_f32_4x4x4_16b_bf16 v[56:59], v[116:117], v[132:133], v[56:59]
	v_mfma_f32_4x4x4_16b_bf16 v[60:63], v[116:117], v[134:135], v[60:63]
	s_waitcnt lgkmcnt(4)
	v_mfma_f32_32x32x16_bf16 v[32:47], v[148:151], v[132:135], v[32:47]
	v_mfma_f32_4x4x4_16b_bf16 v[48:51], v[116:117], v[136:137], v[48:51]
	v_mfma_f32_4x4x4_16b_bf16 v[52:55], v[116:117], v[138:139], v[52:55]
	s_waitcnt lgkmcnt(2)
	v_mfma_f32_32x32x16_bf16 v[32:47], v[152:155], v[136:139], v[32:47]
	v_mfma_f32_4x4x4_16b_bf16 v[56:59], v[116:117], v[140:141], v[56:59]
	v_mfma_f32_4x4x4_16b_bf16 v[60:63], v[116:117], v[142:143], v[60:63]
	s_waitcnt lgkmcnt(0)
	v_mfma_f32_32x32x16_bf16 v[32:47], v[156:159], v[140:143], v[32:47]
	s_setprio 0
	s_branch .Lna_next

.Lna_541:
	v_exp_f32_e32 v0, v14
	v_exp_f32_e32 v14, v15
	v_exp_f32_e32 v15, v80
	v_exp_f32_e32 v81, v81
	v_exp_f32_e32 v82, v82
	v_exp_f32_e32 v83, v83
	v_exp_f32_e32 v94, v84
	v_exp_f32_e32 v95, v85
	v_exp_f32_e32 v84, v86
	v_exp_f32_e32 v85, v87
	v_exp_f32_e32 v86, v88
	v_exp_f32_e32 v87, v89
	v_exp_f32_e32 v88, v90
	v_exp_f32_e32 v89, v91
	v_exp_f32_e32 v90, v92
	v_exp_f32_e32 v91, v93
	v_cvt_pk_bf16_f32 v80, v0, v14
	v_cvt_pk_bf16_f32 v84, v84, v85
	v_cvt_pk_bf16_f32 v81, v15, v81
	v_cvt_pk_bf16_f32 v85, v86, v87
	v_cvt_pk_bf16_f32 v82, v82, v83
	v_cvt_pk_bf16_f32 v86, v88, v89
	v_cvt_pk_bf16_f32 v83, v94, v95
	v_cvt_pk_bf16_f32 v87, v90, v91
	s_setprio 1
	s_waitcnt lgkmcnt(0)
	v_mfma_f32_32x32x16_bf16 v[32:47], v[10:13], v[80:83], v[32:47]
	v_mfma_f32_32x32x16_bf16 v[32:47], v[6:9], v[84:87], v[32:47]
	v_mfma_f32_32x32x16_bf16 v[16:31], v[96:99], v[80:83], v[16:31]
	v_mfma_f32_4x4x4_16b_bf16 v[48:51], v[116:117], v[80:81], v[48:51]
	v_mfma_f32_4x4x4_16b_bf16 v[52:55], v[116:117], v[82:83], v[52:55]
	v_mfma_f32_4x4x4_16b_bf16 v[56:59], v[116:117], v[84:85], v[56:59]
	v_mfma_f32_4x4x4_16b_bf16 v[60:63], v[116:117], v[86:87], v[60:63]
	v_mfma_f32_32x32x16_bf16 v[16:31], v[2:5], v[84:87], v[16:31]
	s_setprio 0
.Lna_next:
	s_add_i32 s83, s83, 1
	s_addk_i32 s51, 0x4000
	s_add_i32 s50, s50, 64
	s_add_i32 s0, s86, s83
	s_cmp_lg_u32 s0, 2
	s_cbranch_scc1 .LBB0_528
	s_nop 15
	v_mov_b64_e32 v[80:81], v[16:17]
	v_mov_b64_e32 v[82:83], v[18:19]
	v_mov_b64_e32 v[84:85], v[20:21]
	v_mov_b64_e32 v[86:87], v[22:23]
	v_mov_b64_e32 v[88:89], v[24:25]
	v_mov_b64_e32 v[90:91], v[26:27]
	v_mov_b64_e32 v[92:93], v[28:29]
	v_mov_b64_e32 v[94:95], v[30:31]
	v_mov_b64_e32 v[96:97], v[32:33]
	v_mov_b64_e32 v[98:99], v[34:35]
	v_mov_b64_e32 v[100:101], v[36:37]
	v_mov_b64_e32 v[102:103], v[38:39]
	v_mov_b64_e32 v[104:105], v[40:41]
	v_mov_b64_e32 v[106:107], v[42:43]
	v_mov_b64_e32 v[108:109], v[44:45]
	v_mov_b64_e32 v[110:111], v[46:47]
	v_add_f32_e32 v48, v48, v52
	v_add_f32_e32 v56, v56, v60
	v_add_f32_e32 v160, v48, v56
	v_mov_b32_e32 v48, v160
	s_nop 1
	v_permlane32_swap_b32_e32 v48, v160
	s_nop 1
	v_add_f32_e32 v160, v160, v48
	s_branch .LBB0_489
	s_nop 0
	s_nop 0
